# w_out GEMM EpiResid epilogue also de-serialised (same software-pipelined RMW, SADDR offsets)
# speedup vs baseline: 1.0196x; 1.0034x over previous
.LBB0_792:
	v_or_b32_e32 v130, s24, v1
	v_add_u32_e32 v130, s35, v130
	v_lshl_or_b32 v186, s2, 8, v201
	v_readlane_b32 s2, v254, 9
	v_or_b32_e32 v162, 16, v130
	v_ashrrev_i32_e32 v131, 31, v130
	v_readlane_b32 s3, v254, 10
	v_ashrrev_i32_e32 v163, 31, v162
	s_lshl_b64 s[24:25], s[26:27], 2
	v_lshl_add_u64 v[132:133], v[130:131], 3, s[2:3]
	v_lshl_add_u64 v[162:163], v[162:163], 3, s[2:3]
	global_load_dwordx2 v[176:177], v[132:133], off
	global_load_dwordx2 v[174:175], v[162:163], off
	v_or_b32_e32 v162, 32, v130
	v_or_b32_e32 v130, 48, v130
	v_ashrrev_i32_e32 v163, 31, v162
	v_ashrrev_i32_e32 v131, 31, v130
	v_lshl_add_u64 v[162:163], v[162:163], 3, s[2:3]
	v_lshl_add_u64 v[130:131], v[130:131], 3, s[2:3]
	v_readlane_b32 s2, v254, 35
	s_add_u32 s24, s2, s24
	v_readlane_b32 s2, v254, 36
	v_ashrrev_i32_e32 v187, 31, v186
	s_addc_u32 s25, s2, s25
	v_readlane_b32 s2, v254, 11
	v_lshlrev_b64 v[178:179], 2, v[186:187]
	v_readlane_b32 s3, v254, 12
	global_load_dwordx2 v[172:173], v[162:163], off
	global_load_dwordx2 v[170:171], v[130:131], off
	global_load_dwordx2 v[168:169], v[132:133], off offset:1024
	global_load_dwordx2 v[166:167], v[132:133], off offset:1152
	global_load_dwordx2 v[164:165], v[132:133], off offset:1280
	s_nop 0
	global_load_dwordx2 v[162:163], v[132:133], off offset:1408
	v_lshl_add_u64 v[184:185], s[2:3], 0, v[178:179]
	v_readlane_b32 s2, v254, 15
	v_readlane_b32 s3, v254, 16
	v_lshl_add_u64 v[182:183], s[24:25], 0, v[178:179]
	v_lshl_add_u64 v[180:181], s[2:3], 0, v[178:179]
	global_load_dwordx4 v[130:133], v[182:183], off
	global_load_dwordx4 v[192:195], v[184:185], off
	global_load_dwordx4 v[196:199], v[180:181], off
	v_add_lshl_u32 v208, v142, v186, 2
	v_add_lshl_u32 v209, v146, v186, 2
	v_add_lshl_u32 v210, v148, v186, 2
	v_add_lshl_u32 v211, v150, v186, 2
	v_add_lshl_u32 v212, v144, v186, 2
	v_add_lshl_u32 v213, v152, v186, 2
	v_add_lshl_u32 v214, v154, v186, 2
	v_add_lshl_u32 v215, v156, v186, 2
	global_load_dwordx4 v[236:239], v208, s[22:23]
	global_load_dwordx4 v[240:243], v209, s[22:23]
	global_load_dwordx4 v[244:247], v210, s[22:23]
	global_load_dwordx4 v[204:207], v211, s[22:23]
	global_load_dwordx4 v[216:219], v212, s[22:23]
	s_waitcnt vmcnt(5)
	v_pk_mul_f32 v[192:193], v[192:193], s[54:55] op_sel_hi:[1,0]
	v_pk_mul_f32 v[194:195], v[194:195], s[54:55] op_sel_hi:[1,0]
	v_pk_mul_f32 v[196:197], v[196:197], s[54:55] op_sel_hi:[1,0]
	v_pk_mul_f32 v[198:199], v[198:199], s[54:55] op_sel_hi:[1,0]
	s_waitcnt vmcnt(4)
	v_sub_f32_e32 v239, v239, v176
	v_sub_f32_e32 v238, v238, v176
	v_sub_f32_e32 v237, v237, v176
	v_sub_f32_e32 v236, v236, v176
	v_pk_mul_f32 v[236:237], v[176:177], v[236:237] op_sel:[1,0]
	v_pk_mul_f32 v[238:239], v[176:177], v[238:239] op_sel:[1,0]
	v_pk_fma_f32 v[236:237], v[192:193], v[236:237], v[196:197]
	v_pk_fma_f32 v[238:239], v[194:195], v[238:239], v[198:199]
	v_pk_fma_f32 v[126:127], v[126:127], v[130:131], v[236:237]
	v_pk_fma_f32 v[128:129], v[128:129], v[132:133], v[238:239]
	global_store_dwordx4 v208, v[126:129], s[22:23]
	global_load_dwordx4 v[236:239], v213, s[22:23]
	global_load_dwordx4 v[126:129], v214, s[22:23]
	s_waitcnt vmcnt(6)
	v_sub_f32_e32 v243, v243, v174
	v_sub_f32_e32 v242, v242, v174
	v_sub_f32_e32 v241, v241, v174
	v_sub_f32_e32 v240, v240, v174
	v_pk_mul_f32 v[240:241], v[174:175], v[240:241] op_sel:[1,0]
	v_pk_mul_f32 v[242:243], v[174:175], v[242:243] op_sel:[1,0]
	v_pk_fma_f32 v[240:241], v[192:193], v[240:241], v[196:197]
	v_pk_fma_f32 v[242:243], v[194:195], v[242:243], v[198:199]
	v_pk_fma_f32 v[122:123], v[122:123], v[130:131], v[240:241]
	v_pk_fma_f32 v[124:125], v[124:125], v[132:133], v[242:243]
	global_store_dwordx4 v209, v[122:125], s[22:23]
	global_load_dwordx4 v[240:243], v215, s[22:23]
	s_waitcnt vmcnt(7)
	v_sub_f32_e32 v247, v247, v172
	v_sub_f32_e32 v246, v246, v172
	v_sub_f32_e32 v245, v245, v172
	v_sub_f32_e32 v244, v244, v172
	v_pk_mul_f32 v[244:245], v[172:173], v[244:245] op_sel:[1,0]
	v_pk_mul_f32 v[246:247], v[172:173], v[246:247] op_sel:[1,0]
	v_pk_fma_f32 v[244:245], v[192:193], v[244:245], v[196:197]
	v_pk_fma_f32 v[246:247], v[194:195], v[246:247], v[198:199]
	v_pk_fma_f32 v[118:119], v[118:119], v[130:131], v[244:245]
	v_pk_fma_f32 v[120:121], v[120:121], v[132:133], v[246:247]
	global_store_dwordx4 v210, v[118:121], s[22:23]
	global_load_dwordx4 v[122:125], v[182:183], off offset:16
	global_load_dwordx4 v[244:247], v[184:185], off offset:16
	global_load_dwordx4 v[118:121], v[180:181], off offset:16
	s_waitcnt vmcnt(10)
	v_sub_f32_e32 v207, v207, v170
	v_sub_f32_e32 v206, v206, v170
	v_sub_f32_e32 v205, v205, v170
	v_sub_f32_e32 v204, v204, v170
	v_pk_mul_f32 v[204:205], v[170:171], v[204:205] op_sel:[1,0]
	v_pk_mul_f32 v[206:207], v[170:171], v[206:207] op_sel:[1,0]
	v_pk_fma_f32 v[204:205], v[192:193], v[204:205], v[196:197]
	v_pk_fma_f32 v[206:207], v[194:195], v[206:207], v[198:199]
	v_pk_fma_f32 v[114:115], v[114:115], v[130:131], v[204:205]
	v_pk_fma_f32 v[116:117], v[116:117], v[132:133], v[206:207]
	global_store_dwordx4 v211, v[114:117], s[22:23]
	global_load_dwordx4 v[204:207], v208, s[22:23] offset:16
	global_load_dwordx4 v[114:117], v209, s[22:23] offset:16
	s_waitcnt vmcnt(12)
	v_sub_f32_e32 v219, v219, v168
	v_sub_f32_e32 v218, v218, v168
	v_sub_f32_e32 v217, v217, v168
	v_sub_f32_e32 v216, v216, v168
	v_pk_mul_f32 v[216:217], v[168:169], v[216:217] op_sel:[1,0]
	v_pk_mul_f32 v[218:219], v[168:169], v[218:219] op_sel:[1,0]
	v_pk_fma_f32 v[216:217], v[192:193], v[216:217], v[196:197]
	v_pk_fma_f32 v[218:219], v[194:195], v[218:219], v[198:199]
	v_pk_fma_f32 v[110:111], v[110:111], v[130:131], v[216:217]
	v_pk_fma_f32 v[112:113], v[112:113], v[132:133], v[218:219]
	global_store_dwordx4 v212, v[110:113], s[22:23]
	global_load_dwordx4 v[216:219], v210, s[22:23] offset:16
	global_load_dwordx4 v[110:113], v211, s[22:23] offset:16
	s_waitcnt vmcnt(13)
	v_sub_f32_e32 v239, v239, v166
	v_sub_f32_e32 v238, v238, v166
	v_sub_f32_e32 v237, v237, v166
	v_sub_f32_e32 v236, v236, v166
	v_pk_mul_f32 v[236:237], v[166:167], v[236:237] op_sel:[1,0]
	v_pk_mul_f32 v[238:239], v[166:167], v[238:239] op_sel:[1,0]
	v_pk_fma_f32 v[236:237], v[192:193], v[236:237], v[196:197]
	v_pk_fma_f32 v[238:239], v[194:195], v[238:239], v[198:199]
	v_pk_fma_f32 v[106:107], v[106:107], v[130:131], v[236:237]
	v_pk_fma_f32 v[108:109], v[108:109], v[132:133], v[238:239]
	global_store_dwordx4 v213, v[106:109], s[22:23]
	global_load_dwordx4 v[236:239], v212, s[22:23] offset:16
	global_load_dwordx4 v[106:109], v213, s[22:23] offset:16
	s_waitcnt vmcnt(15)
	v_sub_f32_e32 v129, v129, v164
	v_sub_f32_e32 v128, v128, v164
	v_sub_f32_e32 v127, v127, v164
	v_sub_f32_e32 v126, v126, v164
	v_pk_mul_f32 v[126:127], v[164:165], v[126:127] op_sel:[1,0]
	v_pk_mul_f32 v[128:129], v[164:165], v[128:129] op_sel:[1,0]
	v_pk_fma_f32 v[126:127], v[192:193], v[126:127], v[196:197]
	v_pk_fma_f32 v[128:129], v[194:195], v[128:129], v[198:199]
	v_pk_fma_f32 v[102:103], v[102:103], v[130:131], v[126:127]
	v_pk_fma_f32 v[104:105], v[104:105], v[132:133], v[128:129]
	global_store_dwordx4 v214, v[102:105], s[22:23]
	global_load_dwordx4 v[126:129], v214, s[22:23] offset:16
	global_load_dwordx4 v[102:105], v215, s[22:23] offset:16
	s_waitcnt vmcnt(16)
	v_sub_f32_e32 v243, v243, v162
	v_sub_f32_e32 v242, v242, v162
	v_sub_f32_e32 v241, v241, v162
	v_sub_f32_e32 v240, v240, v162
	v_pk_mul_f32 v[240:241], v[162:163], v[240:241] op_sel:[1,0]
	v_pk_mul_f32 v[242:243], v[162:163], v[242:243] op_sel:[1,0]
	v_pk_fma_f32 v[240:241], v[192:193], v[240:241], v[196:197]
	v_pk_fma_f32 v[242:243], v[194:195], v[242:243], v[198:199]
	v_pk_fma_f32 v[94:95], v[94:95], v[130:131], v[240:241]
	v_pk_fma_f32 v[96:97], v[96:97], v[132:133], v[242:243]
	global_store_dwordx4 v215, v[94:97], s[22:23]
	global_load_dwordx4 v[240:243], v[182:183], off offset:512
	global_load_dwordx4 v[94:97], v[184:185], off offset:512
	global_load_dwordx4 v[130:133], v[180:181], off offset:512
	global_load_dwordx4 v[192:195], v208, s[22:23] offset:512
	global_load_dwordx4 v[196:199], v209, s[22:23] offset:512
	s_waitcnt vmcnt(18)
	v_pk_mul_f32 v[244:245], v[244:245], s[54:55] op_sel_hi:[1,0]
	v_pk_mul_f32 v[246:247], v[246:247], s[54:55] op_sel_hi:[1,0]
	v_pk_mul_f32 v[118:119], v[118:119], s[54:55] op_sel_hi:[1,0]
	v_pk_mul_f32 v[120:121], v[120:121], s[54:55] op_sel_hi:[1,0]
	s_waitcnt vmcnt(16)
	v_sub_f32_e32 v207, v207, v176
	v_sub_f32_e32 v206, v206, v176
	v_sub_f32_e32 v205, v205, v176
	v_sub_f32_e32 v204, v204, v176
	v_pk_mul_f32 v[204:205], v[176:177], v[204:205] op_sel:[1,0]
	v_pk_mul_f32 v[206:207], v[176:177], v[206:207] op_sel:[1,0]
	v_pk_fma_f32 v[204:205], v[244:245], v[204:205], v[118:119]
	v_pk_fma_f32 v[206:207], v[246:247], v[206:207], v[120:121]
	v_pk_fma_f32 v[98:99], v[98:99], v[122:123], v[204:205]
	v_pk_fma_f32 v[100:101], v[100:101], v[124:125], v[206:207]
	global_store_dwordx4 v208, v[98:101], s[22:23] offset:16
	global_load_dwordx4 v[204:207], v210, s[22:23] offset:512
	global_load_dwordx4 v[98:101], v211, s[22:23] offset:512
	s_waitcnt vmcnt(18)
	v_sub_f32_e32 v117, v117, v174
	v_sub_f32_e32 v116, v116, v174
	v_sub_f32_e32 v115, v115, v174
	v_sub_f32_e32 v114, v114, v174
	v_pk_mul_f32 v[114:115], v[174:175], v[114:115] op_sel:[1,0]
	v_pk_mul_f32 v[116:117], v[174:175], v[116:117] op_sel:[1,0]
	v_pk_fma_f32 v[114:115], v[244:245], v[114:115], v[118:119]
	v_pk_fma_f32 v[116:117], v[246:247], v[116:117], v[120:121]
	v_pk_fma_f32 v[90:91], v[90:91], v[122:123], v[114:115]
	v_pk_fma_f32 v[92:93], v[92:93], v[124:125], v[116:117]
	global_store_dwordx4 v209, v[90:93], s[22:23] offset:16
	global_load_dwordx4 v[114:117], v212, s[22:23] offset:512
	global_load_dwordx4 v[90:93], v213, s[22:23] offset:512
	s_waitcnt vmcnt(19)
	v_sub_f32_e32 v219, v219, v172
	v_sub_f32_e32 v218, v218, v172
	v_sub_f32_e32 v217, v217, v172
	v_sub_f32_e32 v216, v216, v172
	v_pk_mul_f32 v[216:217], v[172:173], v[216:217] op_sel:[1,0]
	v_pk_mul_f32 v[218:219], v[172:173], v[218:219] op_sel:[1,0]
	v_pk_fma_f32 v[216:217], v[244:245], v[216:217], v[118:119]
	v_pk_fma_f32 v[218:219], v[246:247], v[218:219], v[120:121]
	v_pk_fma_f32 v[86:87], v[86:87], v[122:123], v[216:217]
	v_pk_fma_f32 v[88:89], v[88:89], v[124:125], v[218:219]
	global_store_dwordx4 v210, v[86:89], s[22:23] offset:16
	global_load_dwordx4 v[216:219], v214, s[22:23] offset:512
	global_load_dwordx4 v[86:89], v215, s[22:23] offset:512
	s_waitcnt vmcnt(21)
	v_sub_f32_e32 v113, v113, v170
	v_sub_f32_e32 v112, v112, v170
	v_sub_f32_e32 v111, v111, v170
	v_sub_f32_e32 v110, v110, v170
	v_pk_mul_f32 v[110:111], v[170:171], v[110:111] op_sel:[1,0]
	v_pk_mul_f32 v[112:113], v[170:171], v[112:113] op_sel:[1,0]
	v_pk_fma_f32 v[110:111], v[244:245], v[110:111], v[118:119]
	v_pk_fma_f32 v[112:113], v[246:247], v[112:113], v[120:121]
	v_pk_fma_f32 v[82:83], v[82:83], v[122:123], v[110:111]
	v_pk_fma_f32 v[84:85], v[84:85], v[124:125], v[112:113]
	global_store_dwordx4 v211, v[82:85], s[22:23] offset:16
	s_waitcnt vmcnt(20)
	v_sub_f32_e32 v239, v239, v168
	v_sub_f32_e32 v238, v238, v168
	v_sub_f32_e32 v237, v237, v168
	v_sub_f32_e32 v236, v236, v168
	v_pk_mul_f32 v[236:237], v[168:169], v[236:237] op_sel:[1,0]
	v_pk_mul_f32 v[238:239], v[168:169], v[238:239] op_sel:[1,0]
	v_pk_fma_f32 v[236:237], v[244:245], v[236:237], v[118:119]
	v_pk_fma_f32 v[238:239], v[246:247], v[238:239], v[120:121]
	v_pk_fma_f32 v[78:79], v[78:79], v[122:123], v[236:237]
	v_pk_fma_f32 v[80:81], v[80:81], v[124:125], v[238:239]
	global_store_dwordx4 v212, v[78:81], s[22:23] offset:16
	global_load_dwordx4 v[110:113], v[182:183], off offset:528
	global_load_dwordx4 v[82:85], v[184:185], off offset:528
	global_load_dwordx4 v[236:239], v[180:181], off offset:528
	global_load_dwordx4 v[78:81], v208, s[22:23] offset:528
	s_waitcnt vmcnt(24)
	v_sub_f32_e32 v109, v109, v166
	v_sub_f32_e32 v108, v108, v166
	v_sub_f32_e32 v107, v107, v166
	v_sub_f32_e32 v106, v106, v166
	v_pk_mul_f32 v[106:107], v[166:167], v[106:107] op_sel:[1,0]
	v_pk_mul_f32 v[108:109], v[166:167], v[108:109] op_sel:[1,0]
	v_pk_fma_f32 v[106:107], v[244:245], v[106:107], v[118:119]
	v_pk_fma_f32 v[108:109], v[246:247], v[108:109], v[120:121]
	v_pk_fma_f32 v[74:75], v[74:75], v[122:123], v[106:107]
	v_pk_fma_f32 v[76:77], v[76:77], v[124:125], v[108:109]
	global_store_dwordx4 v213, v[74:77], s[22:23] offset:16
	global_load_dwordx4 v[106:109], v209, s[22:23] offset:528
	global_load_dwordx4 v[74:77], v210, s[22:23] offset:528
	s_waitcnt vmcnt(25)
	v_sub_f32_e32 v129, v129, v164
	v_sub_f32_e32 v128, v128, v164
	v_sub_f32_e32 v127, v127, v164
	v_sub_f32_e32 v126, v126, v164
	v_pk_mul_f32 v[126:127], v[164:165], v[126:127] op_sel:[1,0]
	v_pk_mul_f32 v[128:129], v[164:165], v[128:129] op_sel:[1,0]
	v_pk_fma_f32 v[126:127], v[244:245], v[126:127], v[118:119]
	v_pk_fma_f32 v[128:129], v[246:247], v[128:129], v[120:121]
	v_pk_fma_f32 v[70:71], v[70:71], v[122:123], v[126:127]
	v_pk_fma_f32 v[72:73], v[72:73], v[124:125], v[128:129]
	global_store_dwordx4 v214, v[70:73], s[22:23] offset:16
	global_load_dwordx4 v[126:129], v211, s[22:23] offset:528
	global_load_dwordx4 v[70:73], v212, s[22:23] offset:528
	s_waitcnt vmcnt(27)
	v_sub_f32_e32 v105, v105, v162
	v_sub_f32_e32 v104, v104, v162
	v_sub_f32_e32 v103, v103, v162
	v_sub_f32_e32 v102, v102, v162
	v_pk_mul_f32 v[102:103], v[162:163], v[102:103] op_sel:[1,0]
	v_pk_mul_f32 v[104:105], v[162:163], v[104:105] op_sel:[1,0]
	v_pk_fma_f32 v[102:103], v[244:245], v[102:103], v[118:119]
	v_pk_fma_f32 v[104:105], v[246:247], v[104:105], v[120:121]
	v_pk_fma_f32 v[66:67], v[66:67], v[122:123], v[102:103]
	v_pk_fma_f32 v[68:69], v[68:69], v[124:125], v[104:105]
	global_store_dwordx4 v215, v[66:69], s[22:23] offset:16
	global_load_dwordx4 v[102:105], v213, s[22:23] offset:528
	global_load_dwordx4 v[66:69], v214, s[22:23] offset:528
	global_load_dwordx4 v[122:125], v215, s[22:23] offset:528
	s_waitcnt vmcnt(27)
	v_pk_mul_f32 v[94:95], v[94:95], s[54:55] op_sel_hi:[1,0]
	v_pk_mul_f32 v[96:97], v[96:97], s[54:55] op_sel_hi:[1,0]
	v_pk_mul_f32 v[130:131], v[130:131], s[54:55] op_sel_hi:[1,0]
	v_pk_mul_f32 v[132:133], v[132:133], s[54:55] op_sel_hi:[1,0]
	s_waitcnt vmcnt(26)
	v_sub_f32_e32 v195, v195, v176
	v_sub_f32_e32 v194, v194, v176
	v_sub_f32_e32 v193, v193, v176
	v_sub_f32_e32 v192, v192, v176
	v_pk_mul_f32 v[192:193], v[176:177], v[192:193] op_sel:[1,0]
	v_pk_mul_f32 v[194:195], v[176:177], v[194:195] op_sel:[1,0]
	v_pk_fma_f32 v[192:193], v[94:95], v[192:193], v[130:131]
	v_pk_fma_f32 v[194:195], v[96:97], v[194:195], v[132:133]
	v_pk_fma_f32 v[62:63], v[62:63], v[240:241], v[192:193]
	v_pk_fma_f32 v[64:65], v[64:65], v[242:243], v[194:195]
	global_store_dwordx4 v208, v[62:65], s[22:23] offset:512
	s_waitcnt vmcnt(26)
	v_sub_f32_e32 v199, v199, v174
	v_sub_f32_e32 v198, v198, v174
	v_sub_f32_e32 v197, v197, v174
	v_sub_f32_e32 v196, v196, v174
	v_pk_mul_f32 v[196:197], v[174:175], v[196:197] op_sel:[1,0]
	v_pk_mul_f32 v[198:199], v[174:175], v[198:199] op_sel:[1,0]
	v_pk_fma_f32 v[196:197], v[94:95], v[196:197], v[130:131]
	v_pk_fma_f32 v[198:199], v[96:97], v[198:199], v[132:133]
	v_pk_fma_f32 v[58:59], v[58:59], v[240:241], v[196:197]
	v_pk_fma_f32 v[60:61], v[60:61], v[242:243], v[198:199]
	global_store_dwordx4 v209, v[58:61], s[22:23] offset:512
	s_waitcnt vmcnt(25)
	v_sub_f32_e32 v207, v207, v172
	v_sub_f32_e32 v206, v206, v172
	v_sub_f32_e32 v205, v205, v172
	v_sub_f32_e32 v204, v204, v172
	v_pk_mul_f32 v[204:205], v[172:173], v[204:205] op_sel:[1,0]
	v_pk_mul_f32 v[206:207], v[172:173], v[206:207] op_sel:[1,0]
	v_pk_fma_f32 v[204:205], v[94:95], v[204:205], v[130:131]
	v_pk_fma_f32 v[206:207], v[96:97], v[206:207], v[132:133]
	v_pk_fma_f32 v[54:55], v[54:55], v[240:241], v[204:205]
	v_pk_fma_f32 v[56:57], v[56:57], v[242:243], v[206:207]
	global_store_dwordx4 v210, v[54:57], s[22:23] offset:512
	s_waitcnt vmcnt(25)
	v_sub_f32_e32 v101, v101, v170
	v_sub_f32_e32 v100, v100, v170
	v_sub_f32_e32 v99, v99, v170
	v_sub_f32_e32 v98, v98, v170
	v_pk_mul_f32 v[98:99], v[170:171], v[98:99] op_sel:[1,0]
	v_pk_mul_f32 v[100:101], v[170:171], v[100:101] op_sel:[1,0]
	v_pk_fma_f32 v[98:99], v[94:95], v[98:99], v[130:131]
	v_pk_fma_f32 v[100:101], v[96:97], v[100:101], v[132:133]
	v_pk_fma_f32 v[50:51], v[50:51], v[240:241], v[98:99]
	v_pk_fma_f32 v[52:53], v[52:53], v[242:243], v[100:101]
	global_store_dwordx4 v211, v[50:53], s[22:23] offset:512
	s_waitcnt vmcnt(24)
	v_sub_f32_e32 v117, v117, v168
	v_sub_f32_e32 v116, v116, v168
	v_sub_f32_e32 v115, v115, v168
	v_sub_f32_e32 v114, v114, v168
	v_pk_mul_f32 v[114:115], v[168:169], v[114:115] op_sel:[1,0]
	v_pk_mul_f32 v[116:117], v[168:169], v[116:117] op_sel:[1,0]
	v_pk_fma_f32 v[114:115], v[94:95], v[114:115], v[130:131]
	v_pk_fma_f32 v[116:117], v[96:97], v[116:117], v[132:133]
	v_pk_fma_f32 v[46:47], v[46:47], v[240:241], v[114:115]
	v_pk_fma_f32 v[48:49], v[48:49], v[242:243], v[116:117]
	global_store_dwordx4 v212, v[46:49], s[22:23] offset:512
	s_waitcnt vmcnt(24)
	v_sub_f32_e32 v93, v93, v166
	v_sub_f32_e32 v92, v92, v166
	v_sub_f32_e32 v91, v91, v166
	v_sub_f32_e32 v90, v90, v166
	v_pk_mul_f32 v[90:91], v[166:167], v[90:91] op_sel:[1,0]
	v_pk_mul_f32 v[92:93], v[166:167], v[92:93] op_sel:[1,0]
	v_pk_fma_f32 v[90:91], v[94:95], v[90:91], v[130:131]
	v_pk_fma_f32 v[92:93], v[96:97], v[92:93], v[132:133]
	v_pk_fma_f32 v[42:43], v[42:43], v[240:241], v[90:91]
	v_pk_fma_f32 v[44:45], v[44:45], v[242:243], v[92:93]
	global_store_dwordx4 v213, v[42:45], s[22:23] offset:512
	s_waitcnt vmcnt(23)
	v_sub_f32_e32 v219, v219, v164
	v_sub_f32_e32 v218, v218, v164
	v_sub_f32_e32 v217, v217, v164
	v_sub_f32_e32 v216, v216, v164
	v_pk_mul_f32 v[216:217], v[164:165], v[216:217] op_sel:[1,0]
	v_pk_mul_f32 v[218:219], v[164:165], v[218:219] op_sel:[1,0]
	v_pk_fma_f32 v[216:217], v[94:95], v[216:217], v[130:131]
	v_pk_fma_f32 v[218:219], v[96:97], v[218:219], v[132:133]
	v_pk_fma_f32 v[38:39], v[38:39], v[240:241], v[216:217]
	v_pk_fma_f32 v[40:41], v[40:41], v[242:243], v[218:219]
	global_store_dwordx4 v214, v[38:41], s[22:23] offset:512
	s_waitcnt vmcnt(23)
	v_sub_f32_e32 v89, v89, v162
	v_sub_f32_e32 v88, v88, v162
	v_sub_f32_e32 v87, v87, v162
	v_sub_f32_e32 v86, v86, v162
	v_pk_mul_f32 v[86:87], v[162:163], v[86:87] op_sel:[1,0]
	v_pk_mul_f32 v[88:89], v[162:163], v[88:89] op_sel:[1,0]
	v_pk_fma_f32 v[86:87], v[94:95], v[86:87], v[130:131]
	v_pk_fma_f32 v[88:89], v[96:97], v[88:89], v[132:133]
	v_pk_fma_f32 v[30:31], v[30:31], v[240:241], v[86:87]
	v_pk_fma_f32 v[32:33], v[32:33], v[242:243], v[88:89]
	global_store_dwordx4 v215, v[30:33], s[22:23] offset:512
	s_waitcnt vmcnt(19)
	v_pk_mul_f32 v[82:83], v[82:83], s[54:55] op_sel_hi:[1,0]
	v_pk_mul_f32 v[84:85], v[84:85], s[54:55] op_sel_hi:[1,0]
	v_pk_mul_f32 v[236:237], v[236:237], s[54:55] op_sel_hi:[1,0]
	v_pk_mul_f32 v[238:239], v[238:239], s[54:55] op_sel_hi:[1,0]
	s_waitcnt vmcnt(18)
	v_sub_f32_e32 v81, v81, v176
	v_sub_f32_e32 v80, v80, v176
	v_sub_f32_e32 v79, v79, v176
	v_sub_f32_e32 v78, v78, v176
	v_pk_mul_f32 v[78:79], v[176:177], v[78:79] op_sel:[1,0]
	v_pk_mul_f32 v[80:81], v[176:177], v[80:81] op_sel:[1,0]
	v_pk_fma_f32 v[78:79], v[82:83], v[78:79], v[236:237]
	v_pk_fma_f32 v[80:81], v[84:85], v[80:81], v[238:239]
	v_pk_fma_f32 v[34:35], v[34:35], v[110:111], v[78:79]
	v_pk_fma_f32 v[36:37], v[36:37], v[112:113], v[80:81]
	global_store_dwordx4 v208, v[34:37], s[22:23] offset:528
	s_waitcnt vmcnt(17)
	v_sub_f32_e32 v109, v109, v174
	v_sub_f32_e32 v108, v108, v174
	v_sub_f32_e32 v107, v107, v174
	v_sub_f32_e32 v106, v106, v174
	v_pk_mul_f32 v[106:107], v[174:175], v[106:107] op_sel:[1,0]
	v_pk_mul_f32 v[108:109], v[174:175], v[108:109] op_sel:[1,0]
	v_pk_fma_f32 v[106:107], v[82:83], v[106:107], v[236:237]
	v_pk_fma_f32 v[108:109], v[84:85], v[108:109], v[238:239]
	v_pk_fma_f32 v[26:27], v[26:27], v[110:111], v[106:107]
	v_pk_fma_f32 v[28:29], v[28:29], v[112:113], v[108:109]
	global_store_dwordx4 v209, v[26:29], s[22:23] offset:528
	s_waitcnt vmcnt(17)
	v_sub_f32_e32 v77, v77, v172
	v_sub_f32_e32 v76, v76, v172
	v_sub_f32_e32 v75, v75, v172
	v_sub_f32_e32 v74, v74, v172
	v_pk_mul_f32 v[74:75], v[172:173], v[74:75] op_sel:[1,0]
	v_pk_mul_f32 v[76:77], v[172:173], v[76:77] op_sel:[1,0]
	v_pk_fma_f32 v[74:75], v[82:83], v[74:75], v[236:237]
	v_pk_fma_f32 v[76:77], v[84:85], v[76:77], v[238:239]
	v_pk_fma_f32 v[22:23], v[22:23], v[110:111], v[74:75]
	v_pk_fma_f32 v[24:25], v[24:25], v[112:113], v[76:77]
	global_store_dwordx4 v210, v[22:25], s[22:23] offset:528
	s_waitcnt vmcnt(16)
	v_sub_f32_e32 v129, v129, v170
	v_sub_f32_e32 v128, v128, v170
	v_sub_f32_e32 v127, v127, v170
	v_sub_f32_e32 v126, v126, v170
	v_pk_mul_f32 v[126:127], v[170:171], v[126:127] op_sel:[1,0]
	v_pk_mul_f32 v[128:129], v[170:171], v[128:129] op_sel:[1,0]
	v_pk_fma_f32 v[126:127], v[82:83], v[126:127], v[236:237]
	v_pk_fma_f32 v[128:129], v[84:85], v[128:129], v[238:239]
	v_pk_fma_f32 v[18:19], v[18:19], v[110:111], v[126:127]
	v_pk_fma_f32 v[20:21], v[20:21], v[112:113], v[128:129]
	global_store_dwordx4 v211, v[18:21], s[22:23] offset:528
	s_waitcnt vmcnt(16)
	v_sub_f32_e32 v73, v73, v168
	v_sub_f32_e32 v72, v72, v168
	v_sub_f32_e32 v71, v71, v168
	v_sub_f32_e32 v70, v70, v168
	v_pk_mul_f32 v[70:71], v[168:169], v[70:71] op_sel:[1,0]
	v_pk_mul_f32 v[72:73], v[168:169], v[72:73] op_sel:[1,0]
	v_pk_fma_f32 v[70:71], v[82:83], v[70:71], v[236:237]
	v_pk_fma_f32 v[72:73], v[84:85], v[72:73], v[238:239]
	v_pk_fma_f32 v[14:15], v[14:15], v[110:111], v[70:71]
	v_pk_fma_f32 v[16:17], v[16:17], v[112:113], v[72:73]
	global_store_dwordx4 v212, v[14:17], s[22:23] offset:528
	s_waitcnt vmcnt(15)
	v_sub_f32_e32 v105, v105, v166
	v_sub_f32_e32 v104, v104, v166
	v_sub_f32_e32 v103, v103, v166
	v_sub_f32_e32 v102, v102, v166
	v_pk_mul_f32 v[102:103], v[166:167], v[102:103] op_sel:[1,0]
	v_pk_mul_f32 v[104:105], v[166:167], v[104:105] op_sel:[1,0]
	v_pk_fma_f32 v[102:103], v[82:83], v[102:103], v[236:237]
	v_pk_fma_f32 v[104:105], v[84:85], v[104:105], v[238:239]
	v_pk_fma_f32 v[10:11], v[10:11], v[110:111], v[102:103]
	v_pk_fma_f32 v[12:13], v[12:13], v[112:113], v[104:105]
	global_store_dwordx4 v213, v[10:13], s[22:23] offset:528
	s_waitcnt vmcnt(15)
	v_sub_f32_e32 v69, v69, v164
	v_sub_f32_e32 v68, v68, v164
	v_sub_f32_e32 v67, v67, v164
	v_sub_f32_e32 v66, v66, v164
	v_pk_mul_f32 v[66:67], v[164:165], v[66:67] op_sel:[1,0]
	v_pk_mul_f32 v[68:69], v[164:165], v[68:69] op_sel:[1,0]
	v_pk_fma_f32 v[66:67], v[82:83], v[66:67], v[236:237]
	v_pk_fma_f32 v[68:69], v[84:85], v[68:69], v[238:239]
	v_pk_fma_f32 v[6:7], v[6:7], v[110:111], v[66:67]
	v_pk_fma_f32 v[8:9], v[8:9], v[112:113], v[68:69]
	global_store_dwordx4 v214, v[6:9], s[22:23] offset:528
	s_waitcnt vmcnt(15)
	v_sub_f32_e32 v125, v125, v162
	v_sub_f32_e32 v124, v124, v162
	v_sub_f32_e32 v123, v123, v162
	v_sub_f32_e32 v122, v122, v162
	v_pk_mul_f32 v[122:123], v[162:163], v[122:123] op_sel:[1,0]
	v_pk_mul_f32 v[124:125], v[162:163], v[124:125] op_sel:[1,0]
	v_pk_fma_f32 v[122:123], v[82:83], v[122:123], v[236:237]
	v_pk_fma_f32 v[124:125], v[84:85], v[124:125], v[238:239]
	v_pk_fma_f32 v[2:3], v[2:3], v[110:111], v[122:123]
	v_pk_fma_f32 v[4:5], v[4:5], v[112:113], v[124:125]
	global_store_dwordx4 v215, v[2:5], s[22:23] offset:528
	s_mov_b64 s[22:23], -1
	s_andn2_b64 vcc, exec, s[0:1]
	s_cbranch_vccnz .LBB0_781
	s_andn2_b64 vcc, exec, s[4:5]
	s_cbranch_vccnz .LBB0_780
	s_barrier
	s_branch .LBB0_780
